# diff-attention loop: tile sb+2 K/V LDS-DMA moved from the loop-top burst to after QK(a) / QK(b), saddr form, no m0 save/restore
# speedup vs baseline: 1.0119x; 1.0081x over previous
; #define DMA_T(s_) do { DMA_K(s_); DMA_V(s_); } while (0)
; #define CLASSIFY(kv0_, act_, cls_) do { act_ = true; if (SWA) act_ = ((kv0_) + 63 >= qw - 128) && ((kv0_) <= qw + 159); \
;         cls_ = 0; if ((kv0_) + 63 < qw) cls_ = 1; else if ((kv0_) > qw + 31) cls_ = 2; \
;         if (SWA) { if (cls_ == 1 && qw + 31 - (kv0_) > 128) cls_ = 0; if (cls_ == 2 && (kv0_) + 63 - qw > 128) cls_ = 0; } } while (0)
; template <bool SWA>
; __device__ __forceinline__ void unit(LAS unsigned char* lds, const bf16_t* PROJ, const bf16_t* KT, const bf16_t* VT, bf16_t* OB, int opitch, int ocol, int b, int head, int qb, float slope2, float m_init, float lam, const float* subg) {
;     ...
;     for (int S = 0; S < npairs; ++S) {
;         const int sa = 2 * S, sb = 2 * S + 1;
;         if (sa + 2 < nsteps) DMA_T(sa + 2);
;         if (sb + 2 < nsteps) DMA_T(sb + 2);
;         const int kva = TILE_OF(sa) * 64, kvb = TILE_OF(sb < nsteps ? sb : sa) * 64;
;         bool acta, actb; int clsa, clsb;
;         CLASSIFY(kva, acta, clsa); CLASSIFY(kvb, actb, clsb); actb = actb && (sb < nsteps);
;         f32x16 s0, s1, u0, u1;
;         if (acta) QK_T(s0, s1, sa, clsa);
.LBB0_884:
	s_add_i32 s29, s1, -3
	s_add_i32 s27, s1, -2
	s_add_i32 s6, s1, -1
	s_cmp_lt_u32 s29, s0
	s_cselect_b32 s6, s29, s6
	s_mov_b32 s28, s26
	s_lshl_b32 s26, s6, 14
	s_add_u32 s6, s73, s26
	s_addc_u32 s7, s17, 0
	s_add_i32 s30, s25, 0xffffc000
	s_and_b32 s30, s30, 0x8000
	s_add_i32 s31, s30, s33
	v_lshl_add_u64 v[64:65], s[6:7], 0, v[164:165]
	s_mov_b32 s34, m0
	s_mov_b32 m0, s31
	s_nop 0
	global_load_lds_dwordx4 v[64:65], off
	s_mov_b32 m0, s34
	v_lshl_add_u64 v[64:65], s[6:7], 0, v[170:171]
	s_add_i32 s6, s31, 0x400
	s_mov_b32 s7, m0
	s_mov_b32 m0, s6
	s_nop 0
	global_load_lds_dwordx4 v[64:65], off
	s_mov_b32 m0, s7
	s_add_u32 s6, s2, s26
	s_addc_u32 s7, s23, 0
	s_add_i32 s26, s30, s72
	v_lshl_add_u64 v[64:65], s[6:7], 0, v[168:169]
	s_mov_b32 s30, m0
	s_mov_b32 m0, s26
	s_nop 0
	global_load_lds_dwordx4 v[64:65], off
	s_mov_b32 m0, s30
	v_lshl_add_u64 v[64:65], s[6:7], 0, v[172:173]
	s_add_i32 s6, s26, 0x400
	s_cmp_lt_u32 s27, s0
	s_mov_b32 s7, m0
	s_mov_b32 m0, s6
	s_nop 0
	global_load_lds_dwordx4 v[64:65], off
	s_mov_b32 m0, s7
	s_cselect_b32 s6, s27, s1
	s_lshl_b32 s26, s6, 14
	s_add_u32 s98, s73, s26
	s_addc_u32 s99, s17, 0
	s_add_u32 s100, s2, s26
	s_addc_u32 s101, s23, 0
	s_and_b32 s30, s25, 0xc000
	s_add_i32 s32, s30, s33
	s_add_i32 s71, s30, s72
	s_add_i32 s26, s28, 0x80
	s_cmp_gt_u32 s29, s0
	s_cselect_b64 s[78:79], -1, 0
	s_and_b64 s[6:7], s[78:79], exec
	s_cselect_b32 s30, s26, s28
	s_or_b32 s28, s30, 63
	s_cmp_ge_i32 s28, s5
	s_cselect_b64 s[6:7], -1, 0
	s_cmp_lt_i32 s28, s5
	s_cselect_b64 s[82:83], -1, 0
	s_cmp_le_i32 s30, s19
	s_cselect_b64 s[80:81], -1, 0
	s_and_b64 s[84:85], s[6:7], s[80:81]
	s_and_b64 vcc, exec, s[84:85]
	v_mov_b32_e32 v64, 0
	s_cbranch_vccnz .LBB0_886
	s_and_b64 s[28:29], s[80:81], exec
	s_cselect_b32 s28, 0, 64
	s_and_b64 s[6:7], s[6:7], exec
	s_cselect_b32 s6, s28, 0
	s_add_i32 s6, s6, 0
	s_add_i32 s6, s6, 0x20200
	v_mov_b32_e32 v65, s6
	ds_read_b128 v[96:99], v65
	ds_read_b128 v[100:103], v65 offset:16
	ds_read_b128 v[104:107], v65 offset:32
	ds_read_b128 v[108:111], v65 offset:48
	s_branch .LBB0_887

; template <bool SWA>
; __device__ __forceinline__ void unit(LAS unsigned char* lds, const bf16_t* PROJ, const bf16_t* KT, const bf16_t* VT, bf16_t* OB, int opitch, int ocol, int b, int head, int qb, float slope2, float m_init, float lam, const float* subg) {
;     ...
;         if (acta) QK_T(s0, s1, sa, clsa);
;         if (actb) QK_T(u0, u1, sb, clsb);
;         if (acta) { SM_T(s0, s1, kva, clsa); if (pvalid) PV_TILE(sa); }
.LBB0_887:
	s_add_i32 s28, s1, -4
	s_and_b64 s[6:7], s[78:79], exec
	s_cselect_b32 s6, s27, s28
	s_lshl_b32 s28, s6, 6
	s_or_b32 s6, s28, 63
	s_cmp_ge_i32 s6, s5
	s_cselect_b64 s[86:87], -1, 0
	s_cmp_lt_i32 s6, s5
	s_cselect_b64 s[78:79], -1, 0
	s_cmp_le_i32 s28, s19
	s_cselect_b64 s[88:89], -1, 0
	s_add_i32 s6, s25, 0xffff4000
	s_and_b32 s6, s6, 0x8000
	s_add_i32 s29, s6, 0
	v_add_u32_e32 v65, s29, v199
	ds_read_b128 v[66:69], v65
	ds_read_b128 v[70:73], v65 offset:8192
	v_add_u32_e32 v65, s29, v200
	ds_read_b128 v[74:77], v65
	ds_read_b128 v[78:81], v65 offset:8192
	v_add_u32_e32 v65, s29, v201
	ds_read_b128 v[82:85], v65
	ds_read_b128 v[86:89], v65 offset:8192
	v_add_u32_e32 v65, s29, v202
	ds_read_b128 v[90:93], v65
	ds_read_b128 v[204:207], v65 offset:8192
	s_and_b64 s[80:81], s[86:87], s[88:89]
	s_setprio 1
	s_waitcnt lgkmcnt(7)
	v_mfma_f32_32x32x16_bf16 v[112:127], v[66:69], v[140:143], v[96:111]
	s_waitcnt lgkmcnt(6)
	v_mfma_f32_32x32x16_bf16 v[96:111], v[70:73], v[140:143], v[96:111]
	s_waitcnt lgkmcnt(5)
	v_mfma_f32_32x32x16_bf16 v[112:127], v[74:77], v[136:139], v[112:127]
	s_waitcnt lgkmcnt(4)
	v_mfma_f32_32x32x16_bf16 v[96:111], v[78:81], v[136:139], v[96:111]
	s_waitcnt lgkmcnt(3)
	v_mfma_f32_32x32x16_bf16 v[112:127], v[82:85], v[132:135], v[112:127]
	s_waitcnt lgkmcnt(2)
	v_mfma_f32_32x32x16_bf16 v[96:111], v[86:89], v[132:135], v[96:111]
	s_waitcnt lgkmcnt(1)
	v_mfma_f32_32x32x16_bf16 v[112:127], v[90:93], v[128:131], v[112:127]
	s_waitcnt lgkmcnt(0)
	v_mfma_f32_32x32x16_bf16 v[96:111], v[204:207], v[128:131], v[96:111]
	s_setprio 0
	s_mov_b32 m0, s32
	s_nop 0
	global_load_lds_dwordx4 v164, s[98:99]
	s_add_i32 m0, s32, 0x400
	s_nop 0
	global_load_lds_dwordx4 v170, s[98:99]
	s_and_b64 vcc, exec, s[80:81]
	v_mov_b32_e32 v65, 0
	v_mov_b32_e32 v66, 0
	v_mov_b32_e32 v67, 0
	v_mov_b32_e32 v68, 0
	v_mov_b32_e32 v69, 0
	v_mov_b32_e32 v70, 0
	v_mov_b32_e32 v71, 0
	v_mov_b32_e32 v72, 0
	v_mov_b32_e32 v73, 0
	v_mov_b32_e32 v74, 0
	v_mov_b32_e32 v75, 0
	v_mov_b32_e32 v76, 0
	v_mov_b32_e32 v77, 0
	v_mov_b32_e32 v78, 0
	v_mov_b32_e32 v79, 0
	s_cbranch_vccnz .LBB0_889
	s_and_b64 s[6:7], s[88:89], exec
	s_cselect_b32 s27, 0, 64
	s_and_b64 s[6:7], s[86:87], exec
	s_cselect_b32 s6, s27, 0
	s_add_i32 s6, s6, 0
	s_add_i32 s6, s6, 0x20200
	v_mov_b32_e32 v76, s6
	ds_read_b128 v[64:67], v76
	ds_read_b128 v[68:71], v76 offset:16
	ds_read_b128 v[72:75], v76 offset:32
	ds_read_b128 v[76:79], v76 offset:48
.LBB0_889:
	s_add_i32 s6, s25, 0xffff8000
	s_and_b32 s6, s6, 0xc000
	s_add_i32 s27, s6, 0
	v_add_u32_e32 v80, s27, v199
	ds_read_b128 v[204:207], v80
	ds_read_b128 v[208:211], v80 offset:8192
	v_add_u32_e32 v80, s27, v200
	ds_read_b128 v[212:215], v80
	ds_read_b128 v[216:219], v80 offset:8192
	v_add_u32_e32 v80, s27, v201
	ds_read_b128 v[220:223], v80
	ds_read_b128 v[224:227], v80 offset:8192
	v_add_u32_e32 v80, s27, v202
	ds_read_b128 v[228:231], v80
	ds_read_b128 v[232:235], v80 offset:8192
	s_xor_b64 s[34:35], s[84:85], -1
	s_setprio 1
	s_waitcnt lgkmcnt(7)
	v_mfma_f32_32x32x16_bf16 v[80:95], v[204:207], v[140:143], v[64:79]
	s_waitcnt lgkmcnt(6)
	v_mfma_f32_32x32x16_bf16 v[64:79], v[208:211], v[140:143], v[64:79]
	s_waitcnt lgkmcnt(5)
	v_mfma_f32_32x32x16_bf16 v[80:95], v[212:215], v[136:139], v[80:95]
	s_waitcnt lgkmcnt(4)
	v_mfma_f32_32x32x16_bf16 v[64:79], v[216:219], v[136:139], v[64:79]
	s_waitcnt lgkmcnt(3)
	v_mfma_f32_32x32x16_bf16 v[80:95], v[220:223], v[132:135], v[80:95]
	s_waitcnt lgkmcnt(2)
	v_mfma_f32_32x32x16_bf16 v[64:79], v[224:227], v[132:135], v[64:79]
	s_waitcnt lgkmcnt(1)
	v_mfma_f32_32x32x16_bf16 v[80:95], v[228:231], v[128:131], v[80:95]
	s_waitcnt lgkmcnt(0)
	v_mfma_f32_32x32x16_bf16 v[64:79], v[232:235], v[128:131], v[64:79]
	s_setprio 0
	s_mov_b32 m0, s71
	s_nop 0
	global_load_lds_dwordx4 v168, s[100:101]
	s_add_i32 m0, s71, 0x400
	s_nop 0
	global_load_lds_dwordx4 v172, s[100:101]
	v_or_b32_e32 v174, s30, v187
	v_sub_u32_e32 v174, v188, v174
	v_cvt_f32_i32_e32 v174, v174
	s_mov_b64 s[6:7], -1
	s_and_b64 vcc, exec, s[34:35]
	s_cbranch_vccz .LBB0_895
	s_andn2_b64 vcc, exec, s[82:83]
	s_cbranch_vccnz .LBB0_892
	v_mul_f32_e64 v204, -s76, v174
	v_fma_f32 v205, -s76, v174, v194
	s_mov_b64 s[6:7], 0

; __global__ void __launch_bounds__(512, 2) fwd_megakernel(Args a) {
	.amdhsa_kernel _Z14fwd_megakernel4Args
		.amdhsa_group_segment_fixed_size 0
		.amdhsa_private_segment_fixed_size 0
		.amdhsa_kernarg_size 424
		.amdhsa_user_sgpr_count 2
		.amdhsa_user_sgpr_dispatch_ptr 0
		.amdhsa_user_sgpr_queue_ptr 0
		.amdhsa_user_sgpr_kernarg_segment_ptr 1
		.amdhsa_user_sgpr_dispatch_id 0
		.amdhsa_user_sgpr_kernarg_preload_length 0
		.amdhsa_user_sgpr_kernarg_preload_offset 0
		.amdhsa_user_sgpr_private_segment_size 0
		.amdhsa_uses_dynamic_stack 0
		.amdhsa_enable_private_segment 0
		.amdhsa_system_sgpr_workgroup_id_x 1
		.amdhsa_system_sgpr_workgroup_id_y 0
		.amdhsa_system_sgpr_workgroup_id_z 0
		.amdhsa_system_sgpr_workgroup_info 0
		.amdhsa_system_vgpr_workitem_id 2
		.amdhsa_next_free_vgpr 256
		.amdhsa_next_free_sgpr 102
		.amdhsa_accum_offset 256
		.amdhsa_reserve_vcc 1
		.amdhsa_float_round_mode_32 0
		.amdhsa_float_round_mode_16_64 0
		.amdhsa_float_denorm_mode_32 3
		.amdhsa_float_denorm_mode_16_64 3
		.amdhsa_dx10_clamp 1
		.amdhsa_ieee_mode 1
		.amdhsa_fp16_overflow 0
		.amdhsa_tg_split 0
		.amdhsa_exception_fp_ieee_invalid_op 0
		.amdhsa_exception_fp_denorm_src 0
		.amdhsa_exception_fp_ieee_div_zero 0
		.amdhsa_exception_fp_ieee_overflow 0
		.amdhsa_exception_fp_ieee_underflow 0
		.amdhsa_exception_fp_ieee_inexact 0
		.amdhsa_exception_int_div_zero 0
	.end_amdhsa_kernel

; __global__ void __launch_bounds__(512, 2) fwd_megakernel(Args a) {
amdhsa.kernels:
  - .agpr_count:     0
    .args:
      - .offset:         0
        .size:           168
        .value_kind:     by_value
      - .offset:         168
        .size:           4
        .value_kind:     hidden_block_count_x
      - .offset:         172
        .size:           4
        .value_kind:     hidden_block_count_y
      - .offset:         176
        .size:           4
        .value_kind:     hidden_block_count_z
      - .offset:         180
        .size:           2
        .value_kind:     hidden_group_size_x
      - .offset:         182
        .size:           2
        .value_kind:     hidden_group_size_y
      - .offset:         184
        .size:           2
        .value_kind:     hidden_group_size_z
      - .offset:         186
        .size:           2
        .value_kind:     hidden_remainder_x
      - .offset:         188
        .size:           2
        .value_kind:     hidden_remainder_y
      - .offset:         190
        .size:           2
        .value_kind:     hidden_remainder_z
      - .offset:         208
        .size:           8
        .value_kind:     hidden_global_offset_x
      - .offset:         216
        .size:           8
        .value_kind:     hidden_global_offset_y
      - .offset:         224
        .size:           8
        .value_kind:     hidden_global_offset_z
      - .offset:         232
        .size:           2
        .value_kind:     hidden_grid_dims
      - .offset:         256
        .size:           8
        .value_kind:     hidden_multigrid_sync_arg
      - .offset:         288
        .size:           4
        .value_kind:     hidden_dynamic_lds_size
    .group_segment_fixed_size: 0
    .kernarg_segment_align: 8
    .kernarg_segment_size: 424
    .language:       OpenCL C
    .language_version:
      - 2
      - 0
    .max_flat_workgroup_size: 512
    .name:           _Z14fwd_megakernel4Args
    .private_segment_fixed_size: 0
    .sgpr_count:     108
    .sgpr_spill_count: 81
    .symbol:         _Z14fwd_megakernel4Args.kd
    .uniform_work_group_size: 1
    .uses_dynamic_stack: false
    .vgpr_count:     256
    .vgpr_spill_count: 0
    .wavefront_size: 64
